# odd workgroups run their split-K piece first in G3/G5 (unit order swap) to de-synchronise f32 epilogue bursts; on top of G2 in-register gated merge
# speedup vs baseline: 1.0234x; 1.0013x over previous
; __device__ __forceinline__ bool next_unit(const Params& p, int gph, int i, Unit& u) {
;     ...
;   } else if (gph == 2) {
;     const int v = i * G + c; if (v >= 512) return false;
;     if (v < 256) {
;       static_tile(36, 8, v, u.pm, u.pn);
;       u.A = ws + WS_MERGEDB + (size_t)u.pm * 256 * 2048 * 2; u.B = ws + WS_WOUT + (size_t)u.pn * 256 * 2048 * 2; u.nt = 32; u.kind = 12;
;     } else {
;       const int su = v - 256, s = su & 7; int pm, pn;
;       static_tile(36, 8, 256 + (su >> 3), pm, pn);
;       u.A = ws + WS_MERGEDB + ((size_t)pm * 256 * 2048 + s * 256) * 2; u.B = ws + WS_WOUT + ((size_t)pn * 256 * 2048 + s * 256) * 2; u.nt = 4; u.kind = 16;
;       u.pm = su; u.pn = 0;
;     }
;     return true;
;   } else if (gph == 3) {
;     const int L = i * G + c;
;     if (G == 256 && L >= 1536) {
;       const int su = L - 1536; if (su >= 192) return false;
;       int pm, pn; static_tile(36, 44, 1536 + (su >> 2), pm, pn);
;       const size_t ko = (size_t)(su & 3) * 512;
;       u.A = ws + WS_X1B + ((size_t)pm * 256 * 2048 + ko) * 2; u.B = ws + WS_WGU + ((size_t)pn * 256 * 2048 + ko) * 2; u.nt = 8; u.kind = 16;
;       u.pm = su; u.pn = 0;
;       return true;
;     }
;     if (L >= 1584) return false;
;     static_tile(36, 44, L, u.pm, u.pn);
;     u.A = ws + WS_X1B + (size_t)u.pm * 256 * 2048 * 2; u.B = ws + WS_WGU + (size_t)u.pn * 256 * 2048 * 2; u.nt = 32; u.kind = 13;
;     return true;
;   } else {
;     const int v = i * G + c; if (v >= 512) return false;
;     if (v < 256) {
;       static_tile(36, 8, v, u.pm, u.pn);
;       u.A = ws + WS_ACT + (size_t)u.pm * 256 * 5632 * 2; u.B = ws + WS_WDN + (size_t)u.pn * 256 * 5632 * 2; u.nt = 88; u.kind = 14;
;     } else {
;       const int su = v - 256, s = su & 7; int pm, pn;
;       static_tile(36, 8, 256 + (su >> 3), pm, pn);
;       const int kt0 = s < 4 ? 12 * s : 48 + 10 * (s - 4);
;       u.A = ws + WS_ACT + ((size_t)pm * 256 * 5632 + kt0 * 64) * 2; u.B = ws + WS_WDN + ((size_t)pn * 256 * 5632 + kt0 * 64) * 2; u.nt = s < 4 ? 12 : 10; u.kind = 16;
;       u.pm = su; u.pn = 0;
;     }
.LBB0_290:
	s_mov_b32 s100, 0
	s_cmpk_lg_u32 s28, 0x100
	s_cbranch_scc1 .Lsw_done
	s_bitcmp1_b32 s92, 0
	s_cbranch_scc0 .Lsw_done
	s_cmp_eq_u32 s74, 2
	s_cbranch_scc1 .Lsw_common
	s_cmp_eq_u32 s74, 4
	s_cbranch_scc0 .Lsw_done
.Lsw_common:
	s_movk_i32 s100, 0x100
	s_lshr_b32 s34, s92, 3
	s_and_b32 s35, s34, 7
	s_mul_i32 s35, s35, 36
	s_lshr_b32 s34, s34, 3
	s_add_i32 s34, s34, s35
	s_add_i32 s34, s34, 32
	s_lshr_b32 s35, s34, 6
	s_and_b32 s34, s34, 63
	s_cmp_eq_u32 s35, 4
	s_cbranch_scc1 .Lsw_g4
	s_lshl_b32 s35, s35, 3
	s_and_b32 s40, s34, 7
	s_add_i32 s35, s35, s40
	s_lshr_b32 s34, s34, 3
	s_branch .Lsw_pmpn
.Lsw_g4:
	s_and_b32 s40, s34, 3
	s_add_i32 s35, s40, 32
	s_lshr_b32 s34, s34, 2
.Lsw_pmpn:
	s_and_b32 s29, s92, 7
	s_mov_b32 s76, 16
	s_mov_b32 s78, 0
	s_mov_b32 s48, s92
	s_cmp_eq_u32 s74, 4
	s_cbranch_scc1 .Lsw_g5
	s_mov_b32 s77, 4
	s_lshl_b32 s35, s35, 20
	s_lshl_b32 s29, s29, 9
	s_add_i32 s35, s35, s29
	s_add_u32 s44, s24, 0x17b09000
	s_addc_u32 s45, s25, 0
	s_add_u32 s44, s44, s35
	s_addc_u32 s45, s45, 0
	s_lshl_b32 s34, s34, 20
	s_add_i32 s34, s34, s29
	s_add_u32 s46, s24, 0x7109000
	s_addc_u32 s47, s25, 0
	s_add_u32 s46, s46, s34
	s_addc_u32 s47, s47, 0
	s_branch .Lsw_done
.Lsw_g5:
	s_mul_i32 s40, s29, 12
	s_mov_b32 s77, 12
	s_cmp_lt_u32 s29, 4
	s_cbranch_scc1 .Lsw_kt
	s_mul_i32 s40, s29, 10
	s_add_i32 s40, s40, 8
	s_mov_b32 s77, 10
.Lsw_kt:
	s_lshl_b32 s40, s40, 7
	s_mul_i32 s35, s35, 0x2c0000
	s_add_i32 s35, s35, s40
	s_add_u32 s44, s24, 0xc709000
	s_addc_u32 s45, s25, 0
	s_add_u32 s44, s44, s35
	s_addc_u32 s45, s45, 0
	s_mul_i32 s34, s34, 0x2c0000
	s_add_i32 s34, s34, s40
	s_add_u32 s46, s24, 0xa509000
	s_addc_u32 s47, s25, 0
	s_add_u32 s46, s46, s34
	s_addc_u32 s47, s47, 0

; __device__ __forceinline__ bool next_unit(const Params& p, int gph, int i, Unit& u) {
;     ...
;   } else {
;     const int v = i * G + c; if (v >= 512) return false;
;     if (v < 256) {
;       static_tile(36, 8, v, u.pm, u.pn);
;       u.A = ws + WS_ACT + (size_t)u.pm * 256 * 5632 * 2; u.B = ws + WS_WDN + (size_t)u.pn * 256 * 5632 * 2; u.nt = 88; u.kind = 14;
;     } else {
;       const int su = v - 256, s = su & 7; int pm, pn;
;       static_tile(36, 8, 256 + (su >> 3), pm, pn);
;       const int kt0 = s < 4 ? 12 * s : 48 + 10 * (s - 4);
;       u.A = ws + WS_ACT + ((size_t)pm * 256 * 5632 + kt0 * 64) * 2; u.B = ws + WS_WDN + ((size_t)pn * 256 * 5632 + kt0 * 64) * 2; u.nt = s < 4 ? 12 : 10; u.kind = 16;
;       u.pm = su; u.pn = 0;
;     }
;     return true;
.LBB0_295:
	s_add_i32 s86, s51, 1
	s_mov_b64 s[36:37], s[54:55]
	s_mov_b64 s[38:39], s[56:57]
	s_mov_b32 s35, s87
	s_mov_b32 s40, s52
	s_mov_b32 s29, s88
	s_mov_b32 s34, s53
	s_cmp_lt_i32 s74, 2
	s_mov_b64 s[60:61], -1
	s_cbranch_scc1 .LBB0_325
	s_cmp_lt_i32 s74, 3
	s_cbranch_scc1 .LBB0_316
	s_cmp_lg_u32 s74, 3
	s_cbranch_scc0 .LBB0_307
	s_mul_i32 s41, s86, s28
	s_add_i32 s41, s41, s92
	s_xor_b32 s41, s41, s100
	s_mov_b64 s[60:61], 0
	s_cmpk_gt_i32 s41, 0x1ff
	s_mov_b64 s[58:59], 0
	s_mov_b64 s[54:55], s[36:37]
	s_mov_b64 s[56:57], s[38:39]
	s_mov_b32 s87, s35
	s_mov_b32 s52, s40
	s_mov_b32 s88, s29
	s_mov_b32 s53, s34
	s_cbranch_scc1 .LBB0_307
	s_cmpk_gt_i32 s41, 0xff
	s_mov_b64 s[58:59], -1
	s_cbranch_scc0 .LBB0_305
	s_and_b32 s54, s41, 7
	s_cmp_gt_u32 s54, 3
	s_mov_b64 s[52:53], -1
	s_cbranch_scc0 .LBB0_302
	s_mul_i32 s49, s54, 10
	s_add_i32 s49, s49, 8
	s_mov_b64 s[52:53], 0

; __device__ __forceinline__ bool next_unit(const Params& p, int gph, int i, Unit& u) {
;     ...
;   } else if (gph == 2) {
;     const int v = i * G + c; if (v >= 512) return false;
;     if (v < 256) {
;       static_tile(36, 8, v, u.pm, u.pn);
;       u.A = ws + WS_MERGEDB + (size_t)u.pm * 256 * 2048 * 2; u.B = ws + WS_WOUT + (size_t)u.pn * 256 * 2048 * 2; u.nt = 32; u.kind = 12;
;     } else {
;       const int su = v - 256, s = su & 7; int pm, pn;
;       static_tile(36, 8, 256 + (su >> 3), pm, pn);
;       u.A = ws + WS_MERGEDB + ((size_t)pm * 256 * 2048 + s * 256) * 2; u.B = ws + WS_WOUT + ((size_t)pn * 256 * 2048 + s * 256) * 2; u.nt = 4; u.kind = 16;
;       u.pm = su; u.pn = 0;
;     }
;     return true;
.LBB0_316:
	s_andn2_b64 vcc, exec, s[60:61]
	s_cbranch_vccnz .LBB0_324
	s_mul_i32 s41, s86, s28
	s_add_i32 s41, s41, s92
	s_xor_b32 s41, s41, s100
	s_mov_b64 s[58:59], 0
	s_cmpk_gt_i32 s41, 0x1ff
	s_mov_b64 s[54:55], s[36:37]
	s_mov_b64 s[56:57], s[38:39]
	s_mov_b32 s87, s35
	s_mov_b32 s52, s40
	s_mov_b32 s88, s29
	s_mov_b32 s53, s34
	s_cbranch_scc1 .LBB0_324
	s_cmpk_gt_i32 s41, 0xff
	s_mov_b64 s[58:59], -1
	s_cbranch_scc0 .LBB0_320
	s_add_i32 s52, s41, 0xffffff00
	s_lshr_b32 s49, s52, 3
	s_bfe_u32 s53, s52, 0x30003
	s_addk_i32 s49, 0x100
	s_mul_i32 s53, s53, 36
	s_lshr_b32 s49, s49, 3
	s_add_i32 s49, s49, s53
	s_lshr_b32 s53, s49, 3
	s_and_b32 s53, s53, 0x7f8
	s_sub_i32 s54, 36, s53
	s_min_u32 s56, s54, 8
	v_cvt_f32_ubyte0_e32 v66, s56
	v_rcp_iflag_f32_e32 v67, v66
	s_and_b32 s49, s49, 63
	v_cvt_f32_ubyte0_e32 v64, s49
	s_mov_b64 s[58:59], 0
	v_mul_f32_e32 v67, v64, v67
	v_trunc_f32_e32 v67, v67
	v_fma_f32 v64, -v67, v66, v64
	v_cvt_u32_f32_e32 v67, v67
	v_cmp_ge_f32_e64 s[54:55], |v64|, v66
	s_cmp_lg_u64 s[54:55], 0
	v_readfirstlane_b32 s57, v67
	s_addc_u32 s57, s57, 0
	s_mul_i32 s54, s57, s56
	s_sub_i32 s49, s49, s54
	s_and_b32 s49, s49, 0xff
	s_add_i32 s53, s53, s49
	s_lshl_b32 s49, s41, 9
	s_and_b32 s49, s49, 0xe00
	s_lshl_b32 s53, s53, 20
	s_add_u32 s53, s90, s53
	s_addc_u32 s55, s91, 0
	s_add_u32 s54, s53, s49
	s_addc_u32 s55, s55, 0
	s_and_b32 s53, s57, 0xff
	s_lshl_b32 s53, s53, 20
	v_readlane_b32 s56, v254, 18
	s_add_u32 s53, s56, s53
	v_readlane_b32 s56, v254, 19
	s_addc_u32 s57, s56, 0
	s_add_u32 s56, s53, s49
	s_addc_u32 s57, s57, 0

; #define LAS __attribute__((address_space(3)))
; __global__ void __launch_bounds__(512, 2) fwd_megakernel(Params p) {
;   extern __shared__ __attribute__((aligned(16))) unsigned char shm[];
;   LAS unsigned char* lds = (LAS unsigned char*)shm;
;   cg::grid_group grid = cg::this_grid();
;   unsigned char* ws = p.ws;
;   if (p.ph_hi > 1000) grid.sync();
;   volatile LAS unsigned* xst = (volatile LAS unsigned*)(lds + LDS_CTL - 16);
;   if (threadIdx.x == 0) { xst[0] = 0u; xst[1] = 0u; }
;   __syncthreads();
;   const XcdBarrier xb = xcd_barrier_post((unsigned*)(ws + WS_BAR), xst);
	.amdhsa_kernel _Z14fwd_megakernel6Params
		.amdhsa_group_segment_fixed_size 0
		.amdhsa_private_segment_fixed_size 0
		.amdhsa_kernarg_size 480
		.amdhsa_user_sgpr_count 2
		.amdhsa_user_sgpr_dispatch_ptr 0
		.amdhsa_user_sgpr_queue_ptr 0
		.amdhsa_user_sgpr_kernarg_segment_ptr 1
		.amdhsa_user_sgpr_dispatch_id 0
		.amdhsa_user_sgpr_kernarg_preload_length 0
		.amdhsa_user_sgpr_kernarg_preload_offset 0
		.amdhsa_user_sgpr_private_segment_size 0
		.amdhsa_uses_dynamic_stack 0
		.amdhsa_enable_private_segment 0
		.amdhsa_system_sgpr_workgroup_id_x 1
		.amdhsa_system_sgpr_workgroup_id_y 0
		.amdhsa_system_sgpr_workgroup_id_z 0
		.amdhsa_system_sgpr_workgroup_info 0
		.amdhsa_system_vgpr_workitem_id 2
		.amdhsa_next_free_vgpr 256
		.amdhsa_next_free_sgpr 101
		.amdhsa_accum_offset 256
		.amdhsa_reserve_vcc 1
		.amdhsa_float_round_mode_32 0
		.amdhsa_float_round_mode_16_64 0
		.amdhsa_float_denorm_mode_32 3
		.amdhsa_float_denorm_mode_16_64 3
		.amdhsa_dx10_clamp 1
		.amdhsa_ieee_mode 1
		.amdhsa_fp16_overflow 0
		.amdhsa_tg_split 0
		.amdhsa_exception_fp_ieee_invalid_op 0
		.amdhsa_exception_fp_denorm_src 0
		.amdhsa_exception_fp_ieee_div_zero 0
		.amdhsa_exception_fp_ieee_overflow 0
		.amdhsa_exception_fp_ieee_underflow 0
		.amdhsa_exception_fp_ieee_inexact 0
		.amdhsa_exception_int_div_zero 0
	.end_amdhsa_kernel

; #define LAS __attribute__((address_space(3)))
; __global__ void __launch_bounds__(512, 2) fwd_megakernel(Params p) {
;   extern __shared__ __attribute__((aligned(16))) unsigned char shm[];
;   LAS unsigned char* lds = (LAS unsigned char*)shm;
;   cg::grid_group grid = cg::this_grid();
;   unsigned char* ws = p.ws;
;   if (p.ph_hi > 1000) grid.sync();
;   volatile LAS unsigned* xst = (volatile LAS unsigned*)(lds + LDS_CTL - 16);
;   if (threadIdx.x == 0) { xst[0] = 0u; xst[1] = 0u; }
;   __syncthreads();
;   const XcdBarrier xb = xcd_barrier_post((unsigned*)(ws + WS_BAR), xst);
amdhsa.kernels:
  - .agpr_count:     0
    .args:
      - .offset:         0
        .size:           224
        .value_kind:     by_value
      - .offset:         224
        .size:           4
        .value_kind:     hidden_block_count_x
      - .offset:         228
        .size:           4
        .value_kind:     hidden_block_count_y
      - .offset:         232
        .size:           4
        .value_kind:     hidden_block_count_z
      - .offset:         236
        .size:           2
        .value_kind:     hidden_group_size_x
      - .offset:         238
        .size:           2
        .value_kind:     hidden_group_size_y
      - .offset:         240
        .size:           2
        .value_kind:     hidden_group_size_z
      - .offset:         242
        .size:           2
        .value_kind:     hidden_remainder_x
      - .offset:         244
        .size:           2
        .value_kind:     hidden_remainder_y
      - .offset:         246
        .size:           2
        .value_kind:     hidden_remainder_z
      - .offset:         264
        .size:           8
        .value_kind:     hidden_global_offset_x
      - .offset:         272
        .size:           8
        .value_kind:     hidden_global_offset_y
      - .offset:         280
        .size:           8
        .value_kind:     hidden_global_offset_z
      - .offset:         288
        .size:           2
        .value_kind:     hidden_grid_dims
      - .offset:         312
        .size:           8
        .value_kind:     hidden_multigrid_sync_arg
      - .offset:         344
        .size:           4
        .value_kind:     hidden_dynamic_lds_size
    .group_segment_fixed_size: 0
    .kernarg_segment_align: 8
    .kernarg_segment_size: 480
    .language:       OpenCL C
    .language_version:
      - 2
      - 0
    .max_flat_workgroup_size: 512
    .name:           _Z14fwd_megakernel6Params
    .private_segment_fixed_size: 0
    .sgpr_count:     107
    .sgpr_spill_count: 348
    .symbol:         _Z14fwd_megakernel6Params.kd
    .uniform_work_group_size: 1
    .uses_dynamic_stack: false
    .vgpr_count:     256
    .vgpr_spill_count: 0
    .wavefront_size: 64
